# stack2 plus attention unit epilogue: gamma loads hoisted out of the store chain and the o1-lam*o2 LDS exchange pipelined in groups of eight
# speedup vs baseline: 1.0001x; 1.0001x over previous
; #define LAS __attribute__((address_space(3)))
; __device__ __forceinline__ int crow(int r, int hi) { return (r & 3) + 8 * (r >> 2) + 4 * hi; }
; __device__ __forceinline__ void unit(int b, int h, int qb, const Params& P, LAS unsigned char* lds, const int tid) {
;     ...
;     if (mp == 0) {
; #pragma unroll
;         for (int r = 0; r < 16; ++r)
; #pragma unroll
;             for (int d = 0; d < 4; ++d) { LAS float* xp = X + crow(r, 0) * 136 + (d >> 1) * 68 + (d & 1) * 32; *xp = o[d][r] - P.lam * (*xp); }
;         asm volatile("s_waitcnt lgkmcnt(0)" ::: "memory");
;     ...
;         bf16_t* op = P.O + (rowbase + qa + row) * 2048 + h * 128 + half * 64; const float* gp = P.g + half * 64;
; #pragma unroll
;         for (int k = 0; k < 8; ++k) { const f32x4 g0 = *(const f32x4*)(gp + 8 * k) * rs, g1 = *(const f32x4*)(gp + 8 * k + 4) * rs; const f32x4 a0 = v4[2 * k] * g0, a1 = v4[2 * k + 1] * g1;
.LBB0_115:
	s_waitcnt vmcnt(0) lgkmcnt(0)
	s_barrier
	s_andn2_b64 vcc, exec, s[18:19]
	s_cbranch_vccnz .LBB0_35
	v_and_b32_e32 v100, 1, v230
	v_lshlrev_b32_e32 v100, 8, v100
	global_load_dwordx4 v[112:115], v100, s[40:41]
	global_load_dwordx4 v[116:119], v100, s[40:41] offset:16
	global_load_dwordx4 v[120:123], v100, s[40:41] offset:32
	global_load_dwordx4 v[124:127], v100, s[40:41] offset:48
	global_load_dwordx4 v[128:131], v100, s[40:41] offset:64
	global_load_dwordx4 v[132:135], v100, s[40:41] offset:80
	global_load_dwordx4 v[176:179], v100, s[40:41] offset:96
	global_load_dwordx4 v[180:183], v100, s[40:41] offset:112
	global_load_dwordx4 v[184:187], v100, s[40:41] offset:128
	global_load_dwordx4 v[188:191], v100, s[40:41] offset:144
	global_load_dwordx4 v[208:211], v100, s[40:41] offset:160
	global_load_dwordx4 v[212:215], v100, s[40:41] offset:176
	global_load_dwordx4 v[216:219], v100, s[40:41] offset:192
	global_load_dwordx4 v[232:235], v100, s[40:41] offset:208
	global_load_dwordx4 v[236:239], v100, s[40:41] offset:224
	global_load_dwordx4 v[240:243], v100, s[40:41] offset:240
	s_movk_i32 s12, 0x220
	ds_read2_b32 v[144:145], v41 offset1:32
	ds_read2_b32 v[146:147], v41 offset0:68 offset1:100
	ds_read2_b32 v[148:149], v41 offset0:136 offset1:168
	ds_read2_b32 v[150:151], v41 offset0:204 offset1:236
	ds_read2_b32 v[102:103], v40 offset0:16 offset1:48
	ds_read2_b32 v[104:105], v40 offset0:84 offset1:116
	ds_read2_b32 v[106:107], v40 offset0:152 offset1:184
	ds_read2_b32 v[108:109], v40 offset0:220 offset1:252
	s_waitcnt lgkmcnt(7)
	v_fma_f32 v144, -v161, v144, v90
	v_fma_f32 v145, -v161, v145, v91
	ds_write2_b32 v41, v144, v145 offset1:32
	s_waitcnt lgkmcnt(7)
	v_fma_f32 v146, -v161, v146, v88
	v_fma_f32 v147, -v161, v147, v89
	ds_write2_b32 v41, v146, v147 offset0:68 offset1:100
	s_waitcnt lgkmcnt(7)
	v_fma_f32 v148, -v161, v148, v86
	v_fma_f32 v149, -v161, v149, v87
	ds_write2_b32 v41, v148, v149 offset0:136 offset1:168
	s_waitcnt lgkmcnt(7)
	v_fma_f32 v150, -v161, v150, v84
	v_fma_f32 v151, -v161, v151, v85
	ds_write2_b32 v41, v150, v151 offset0:204 offset1:236
	s_waitcnt lgkmcnt(7)
	v_fma_f32 v102, -v161, v102, v82
	v_fma_f32 v103, -v161, v103, v83
	ds_write2_b32 v40, v102, v103 offset0:16 offset1:48
	s_waitcnt lgkmcnt(7)
	v_fma_f32 v104, -v161, v104, v80
	v_fma_f32 v105, -v161, v105, v81
	ds_write2_b32 v40, v104, v105 offset0:84 offset1:116
	s_waitcnt lgkmcnt(7)
	v_fma_f32 v106, -v161, v106, v78
	v_fma_f32 v107, -v161, v107, v79
	ds_write2_b32 v40, v106, v107 offset0:152 offset1:184
	s_waitcnt lgkmcnt(7)
	v_fma_f32 v108, -v161, v108, v76
	v_fma_f32 v109, -v161, v109, v77
	ds_write2_b32 v40, v108, v109 offset0:220 offset1:252
	ds_read2_b32 v[144:145], v31 offset0:64 offset1:96
	ds_read2_b32 v[146:147], v31 offset0:132 offset1:164
	ds_read2_b32 v[148:149], v31 offset0:200 offset1:232
	ds_read2_b32 v[150:151], v30 offset0:12 offset1:44
	ds_read2_b32 v[102:103], v30 offset0:80 offset1:112
	ds_read2_b32 v[104:105], v30 offset0:148 offset1:180
	ds_read2_b32 v[106:107], v30 offset0:216 offset1:248
	ds_read2_b32 v[108:109], v29 offset0:28 offset1:60
	s_waitcnt lgkmcnt(7)
	v_fma_f32 v144, -v161, v144, v74
	v_fma_f32 v145, -v161, v145, v75
	ds_write2_b32 v31, v144, v145 offset0:64 offset1:96
	s_waitcnt lgkmcnt(7)
	v_fma_f32 v146, -v161, v146, v72
	v_fma_f32 v147, -v161, v147, v73
	ds_write2_b32 v31, v146, v147 offset0:132 offset1:164
	s_waitcnt lgkmcnt(7)
	v_fma_f32 v148, -v161, v148, v70
	v_fma_f32 v149, -v161, v149, v71
	ds_write2_b32 v31, v148, v149 offset0:200 offset1:232
	s_waitcnt lgkmcnt(7)
	v_fma_f32 v150, -v161, v150, v68
	v_fma_f32 v151, -v161, v151, v69
	ds_write2_b32 v30, v150, v151 offset0:12 offset1:44
	s_waitcnt lgkmcnt(7)
	v_fma_f32 v102, -v161, v102, v66
	v_fma_f32 v103, -v161, v103, v67
	ds_write2_b32 v30, v102, v103 offset0:80 offset1:112
	s_waitcnt lgkmcnt(7)
	v_fma_f32 v104, -v161, v104, v53
	v_fma_f32 v105, -v161, v105, v54
	ds_write2_b32 v30, v104, v105 offset0:148 offset1:180
	s_waitcnt lgkmcnt(7)
	v_fma_f32 v106, -v161, v106, v51
	v_fma_f32 v107, -v161, v107, v52
	ds_write2_b32 v30, v106, v107 offset0:216 offset1:248
	s_waitcnt lgkmcnt(7)
	v_fma_f32 v108, -v161, v108, v49
	v_fma_f32 v109, -v161, v109, v50
	ds_write2_b32 v29, v108, v109 offset0:28 offset1:60
	ds_read2_b32 v[144:145], v28 offset0:128 offset1:160
	ds_read2_b32 v[146:147], v28 offset0:196 offset1:228
	ds_read2_b32 v[148:149], v27 offset0:8 offset1:40
	ds_read2_b32 v[150:151], v27 offset0:76 offset1:108
	ds_read2_b32 v[102:103], v27 offset0:144 offset1:176
	ds_read2_b32 v[104:105], v27 offset0:212 offset1:244
	ds_read2_b32 v[106:107], v15 offset0:24 offset1:56
	ds_read2_b32 v[108:109], v15 offset0:92 offset1:124
	s_waitcnt lgkmcnt(7)
	v_fma_f32 v144, -v161, v144, v39
	v_fma_f32 v145, -v161, v145, v48
	ds_write2_b32 v28, v144, v145 offset0:128 offset1:160
	s_waitcnt lgkmcnt(7)
	v_fma_f32 v146, -v161, v146, v37
	v_fma_f32 v147, -v161, v147, v38
	ds_write2_b32 v28, v146, v147 offset0:196 offset1:228
	s_waitcnt lgkmcnt(7)
	v_fma_f32 v148, -v161, v148, v35
	v_fma_f32 v149, -v161, v149, v36
	ds_write2_b32 v27, v148, v149 offset0:8 offset1:40
	s_waitcnt lgkmcnt(7)
	v_fma_f32 v150, -v161, v150, v33
	v_fma_f32 v151, -v161, v151, v34
	ds_write2_b32 v27, v150, v151 offset0:76 offset1:108
	s_waitcnt lgkmcnt(7)
	v_fma_f32 v102, -v161, v102, v32
	v_fma_f32 v103, -v161, v103, v26
	ds_write2_b32 v27, v102, v103 offset0:144 offset1:176
	s_waitcnt lgkmcnt(7)
	v_fma_f32 v104, -v161, v104, v24
	v_fma_f32 v105, -v161, v105, v25
	ds_write2_b32 v27, v104, v105 offset0:212 offset1:244
	s_waitcnt lgkmcnt(7)
; #define LAS __attribute__((address_space(3)))
; __device__ __forceinline__ int crow(int r, int hi) { return (r & 3) + 8 * (r >> 2) + 4 * hi; }
; __device__ __forceinline__ void unit(int b, int h, int qb, const Params& P, LAS unsigned char* lds, const int tid) {
;     ...
;             for (int d = 0; d < 4; ++d) { LAS float* xp = X + crow(r, 0) * 136 + (d >> 1) * 68 + (d & 1) * 32; *xp = o[d][r] - P.lam * (*xp); }
;         asm volatile("s_waitcnt lgkmcnt(0)" ::: "memory");
;         int lane_e = r32_e + 32 * hi_e; const int row = lane_e >> 1, half = lane_e & 1;
;         LAS const f32x4* rp = (LAS const f32x4*)(XB + row * 136 + half * 68);
;         f32x4 v4[16]; float ss = 0.f;
; #pragma unroll
;         for (int k = 0; k < 16; ++k) { v4[k] = rp[k]; ss += (v4[k].x * v4[k].x + v4[k].y * v4[k].y) + (v4[k].z * v4[k].z + v4[k].w * v4[k].w); }
;         ss += __shfl_xor(ss, 1);
	v_fma_f32 v106, -v161, v106, v22
	v_fma_f32 v107, -v161, v107, v23
	ds_write2_b32 v15, v106, v107 offset0:24 offset1:56
	s_waitcnt lgkmcnt(7)
	v_fma_f32 v108, -v161, v108, v20
	v_fma_f32 v109, -v161, v109, v21
	ds_write2_b32 v15, v108, v109 offset0:92 offset1:124
	ds_read2_b32 v[144:145], v14 offset0:192 offset1:224
	ds_read2_b32 v[146:147], v9 offset0:4 offset1:36
	ds_read2_b32 v[148:149], v9 offset0:72 offset1:104
	ds_read2_b32 v[150:151], v9 offset0:140 offset1:172
	ds_read2_b32 v[102:103], v9 offset0:208 offset1:240
	ds_read2_b32 v[104:105], v2 offset0:20 offset1:52
	ds_read2_b32 v[106:107], v2 offset0:88 offset1:120
	ds_read2_b32 v[108:109], v2 offset0:156 offset1:188
	s_waitcnt lgkmcnt(7)
	v_fma_f32 v144, -v161, v144, v18
	v_fma_f32 v145, -v161, v145, v19
	ds_write2_b32 v14, v144, v145 offset0:192 offset1:224
	s_waitcnt lgkmcnt(7)
	v_fma_f32 v146, -v161, v146, v16
	v_fma_f32 v147, -v161, v147, v17
	ds_write2_b32 v9, v146, v147 offset0:4 offset1:36
	s_waitcnt lgkmcnt(7)
	v_fma_f32 v148, -v161, v148, v12
	v_fma_f32 v149, -v161, v149, v13
	ds_write2_b32 v9, v148, v149 offset0:72 offset1:104
	s_waitcnt lgkmcnt(7)
	v_fma_f32 v150, -v161, v150, v10
	v_fma_f32 v151, -v161, v151, v11
	ds_write2_b32 v9, v150, v151 offset0:140 offset1:172
	s_waitcnt lgkmcnt(7)
	v_fma_f32 v102, -v161, v102, v7
	v_fma_f32 v103, -v161, v103, v8
	ds_write2_b32 v9, v102, v103 offset0:208 offset1:240
	s_waitcnt lgkmcnt(7)
	v_fma_f32 v104, -v161, v104, v5
	v_fma_f32 v105, -v161, v105, v6
	ds_write2_b32 v2, v104, v105 offset0:20 offset1:52
	s_waitcnt lgkmcnt(7)
	v_fma_f32 v106, -v161, v106, v3
	v_fma_f32 v107, -v161, v107, v4
	ds_write2_b32 v2, v106, v107 offset0:88 offset1:120
	s_waitcnt lgkmcnt(7)
	v_fma_f32 v108, -v161, v108, v0
	v_fma_f32 v109, -v161, v109, v1
	ds_write2_b32 v2, v108, v109 offset0:156 offset1:188
	v_and_b32_e32 v66, 1, v65
	v_lshlrev_b32_e32 v75, 8, v66
	v_lshl_add_u32 v0, v64, 5, v65
	v_ashrrev_i32_e32 v64, 1, v0
	v_mul_lo_u32 v0, v64, s12
	v_mul_u32_u24_e32 v1, 0x110, v66
	s_waitcnt lgkmcnt(0)
	v_add3_u32 v65, s24, v0, v1
	ds_read_b128 v[16:19], v65
	ds_read_b128 v[12:15], v65 offset:16
	ds_read_b128 v[4:7], v65 offset:32
	ds_read_b128 v[0:3], v65 offset:48
	s_ashr_i32 s12, s39, 31
	s_waitcnt lgkmcnt(3)
	v_pk_mul_f32 v[8:9], v[18:19], v[18:19]
	v_pk_mul_f32 v[10:11], v[16:17], v[16:17]
	s_add_u32 s18, s44, s39
	v_pk_mov_b32 v[20:21], v[10:11], v[8:9] op_sel:[1,0]
	v_mov_b32_e32 v11, v9
	v_pk_add_f32 v[8:9], v[20:21], v[10:11]
	s_waitcnt lgkmcnt(2)
	v_pk_mul_f32 v[10:11], v[14:15], v[14:15]
	v_pk_mul_f32 v[20:21], v[12:13], v[12:13]
	v_pk_add_f32 v[8:9], v[8:9], v[8:9] op_sel:[0,1] op_sel_hi:[1,0]
	v_pk_mov_b32 v[22:23], v[20:21], v[10:11] op_sel:[1,0]
	v_mov_b32_e32 v21, v11
	v_pk_add_f32 v[10:11], v[22:23], v[20:21]
	s_waitcnt lgkmcnt(0)
	v_mul_f32_e32 v20, v0, v0
	v_mul_f32_e32 v21, v1, v1
	v_pk_add_f32 v[10:11], v[10:11], v[10:11] op_sel:[0,1] op_sel_hi:[1,0]
	v_mov_b32_e32 v9, v20
	v_mov_b32_e32 v11, v21
	v_pk_add_f32 v[8:9], v[8:9], v[10:11]
	v_mul_f32_e32 v10, v5, v5
	v_mul_f32_e32 v20, v7, v7
	v_mul_f32_e32 v22, v2, v2
	v_mul_f32_e32 v23, v3, v3
	v_pk_fma_f32 v[10:11], v[4:5], v[4:5], v[10:11] op_sel_hi:[1,1,0]
	v_pk_fma_f32 v[20:21], v[6:7], v[6:7], v[20:21] op_sel_hi:[1,1,0]
	v_mov_b32_e32 v11, v22
	v_mov_b32_e32 v21, v23
	v_pk_add_f32 v[10:11], v[10:11], v[20:21]
	s_addc_u32 s19, s45, s12
	v_pk_add_f32 v[28:29], v[8:9], v[10:11]
	ds_read_b128 v[8:11], v65 offset:64
	v_pk_add_f32 v[28:29], v[28:29], v[28:29] op_sel:[0,1] op_sel_hi:[1,0]
	v_readlane_b32 s12, v251, 12
	v_readlane_b32 s13, v251, 13
	s_waitcnt lgkmcnt(0)
	v_pk_mul_f32 v[20:21], v[10:11], v[10:11]
	v_pk_mul_f32 v[22:23], v[8:9], v[8:9]
	s_nop 0
	v_pk_mov_b32 v[24:25], v[22:23], v[20:21] op_sel:[1,0]
	v_mov_b32_e32 v23, v21
	v_pk_add_f32 v[30:31], v[24:25], v[22:23]
	ds_read_b128 v[24:27], v65 offset:80
	ds_read_b128 v[20:23], v65 offset:96
	v_pk_add_f32 v[30:31], v[30:31], v[30:31] op_sel:[0,1] op_sel_hi:[1,0]
	s_waitcnt lgkmcnt(0)
	v_mul_f32_e32 v32, v20, v20
	v_mul_f32_e32 v33, v21, v21
	v_mov_b32_e32 v29, v32
	v_mov_b32_e32 v31, v33
	v_pk_add_f32 v[28:29], v[28:29], v[30:31]
	v_mul_f32_e32 v30, v25, v25
	v_mul_f32_e32 v32, v27, v27
	v_mul_f32_e32 v34, v22, v22
	v_mul_f32_e32 v35, v23, v23
	v_pk_fma_f32 v[30:31], v[24:25], v[24:25], v[30:31] op_sel_hi:[1,1,0]
	v_pk_fma_f32 v[32:33], v[26:27], v[26:27], v[32:33] op_sel_hi:[1,1,0]
	v_mov_b32_e32 v31, v34
	v_mov_b32_e32 v33, v35
	v_pk_add_f32 v[30:31], v[30:31], v[32:33]
	s_nop 0
	v_pk_add_f32 v[32:33], v[28:29], v[30:31]
	ds_read_b128 v[28:31], v65 offset:112
	ds_read_b128 v[44:47], v65 offset:128
	ds_read_b128 v[52:55], v65 offset:144
	v_pk_add_f32 v[32:33], v[32:33], v[32:33] op_sel:[0,1] op_sel_hi:[1,0]
	ds_read_b128 v[56:59], v65 offset:160
	ds_read_b128 v[60:63], v65 offset:176
	ds_read_b128 v[40:43], v65 offset:192
	s_waitcnt lgkmcnt(5)
	v_pk_mul_f32 v[34:35], v[30:31], v[30:31]
	v_pk_mul_f32 v[36:37], v[28:29], v[28:29]
	ds_read_b128 v[48:51], v65 offset:208
	v_pk_mov_b32 v[38:39], v[36:37], v[34:35] op_sel:[1,0]
	v_mov_b32_e32 v37, v35
	v_pk_add_f32 v[34:35], v[38:39], v[36:37]
	s_waitcnt lgkmcnt(4)
	v_mul_f32_e32 v36, v52, v52
	v_mul_f32_e32 v37, v53, v53
	v_pk_add_f32 v[34:35], v[34:35], v[34:35] op_sel:[0,1] op_sel_hi:[1,0]
	v_mov_b32_e32 v33, v36
	v_mov_b32_e32 v35, v37
	v_pk_add_f32 v[32:33], v[32:33], v[34:35]
	v_mul_f32_e32 v34, v45, v45
	v_mul_f32_e32 v36, v47, v47
	v_mul_f32_e32 v38, v54, v54
	v_mul_f32_e32 v39, v55, v55
	v_pk_fma_f32 v[34:35], v[44:45], v[44:45], v[34:35] op_sel_hi:[1,1,0]
	v_pk_fma_f32 v[36:37], v[46:47], v[46:47], v[36:37] op_sel_hi:[1,1,0]
	v_mov_b32_e32 v35, v38
	v_mov_b32_e32 v37, v39
	v_pk_add_f32 v[34:35], v[34:35], v[36:37]
	s_waitcnt lgkmcnt(3)
; __device__ __forceinline__ void unit(int b, int h, int qb, const Params& P, LAS unsigned char* lds, const int tid) {
;     ...
;         for (int k = 0; k < 16; ++k) { v4[k] = rp[k]; ss += (v4[k].x * v4[k].x + v4[k].y * v4[k].y) + (v4[k].z * v4[k].z + v4[k].w * v4[k].w); }
;         ss += __shfl_xor(ss, 1);
;         const float rs = __builtin_amdgcn_rsqf(ss * (1.0f / 128.0f) + LN_EPS) * P.oscale;
;         bf16_t* op = P.O + (rowbase + qa + row) * 2048 + h * 128 + half * 64; const float* gp = P.g + half * 64;
	v_pk_mul_f32 v[36:37], v[56:57], v[56:57]
	v_pk_add_f32 v[32:33], v[32:33], v[34:35]
	v_pk_mul_f32 v[34:35], v[58:59], v[58:59]
	v_pk_add_f32 v[32:33], v[32:33], v[32:33] op_sel:[0,1] op_sel_hi:[1,0]
	v_pk_mov_b32 v[38:39], v[36:37], v[34:35] op_sel:[1,0]
	v_mov_b32_e32 v37, v35
	v_pk_add_f32 v[34:35], v[38:39], v[36:37]
	s_waitcnt lgkmcnt(1)
	v_mul_f32_e32 v36, v40, v40
	v_mul_f32_e32 v37, v41, v41
	v_pk_add_f32 v[34:35], v[34:35], v[34:35] op_sel:[0,1] op_sel_hi:[1,0]
	v_mov_b32_e32 v33, v36
	v_mov_b32_e32 v35, v37
	v_pk_add_f32 v[32:33], v[32:33], v[34:35]
	v_mul_f32_e32 v34, v61, v61
	v_mul_f32_e32 v36, v63, v63
	v_mul_f32_e32 v38, v42, v42
	v_mul_f32_e32 v39, v43, v43
	v_pk_fma_f32 v[34:35], v[60:61], v[60:61], v[34:35] op_sel_hi:[1,1,0]
	v_pk_fma_f32 v[36:37], v[62:63], v[62:63], v[36:37] op_sel_hi:[1,1,0]
	v_mov_b32_e32 v35, v38
	v_mov_b32_e32 v37, v39
	v_pk_add_f32 v[34:35], v[34:35], v[36:37]
	s_nop 0
	v_pk_add_f32 v[68:69], v[32:33], v[34:35]
	s_waitcnt lgkmcnt(0)
	v_pk_mul_f32 v[32:33], v[50:51], v[50:51]
	v_pk_mul_f32 v[34:35], v[48:49], v[48:49]
	v_pk_add_f32 v[68:69], v[68:69], v[68:69] op_sel:[0,1] op_sel_hi:[1,0]
	v_pk_mov_b32 v[36:37], v[34:35], v[32:33] op_sel:[1,0]
	v_mov_b32_e32 v35, v33
	v_pk_add_f32 v[70:71], v[36:37], v[34:35]
	ds_read_b128 v[36:39], v65 offset:224
	ds_read_b128 v[32:35], v65 offset:240
	v_pk_add_f32 v[70:71], v[70:71], v[70:71] op_sel:[0,1] op_sel_hi:[1,0]
	s_waitcnt lgkmcnt(0)
	v_mul_f32_e32 v65, v32, v32
	v_mul_f32_e32 v67, v33, v33
	v_mov_b32_e32 v69, v65
	v_mov_b32_e32 v71, v67
	v_pk_add_f32 v[68:69], v[68:69], v[70:71]
	v_mul_f32_e32 v70, v37, v37
	v_mul_f32_e32 v72, v34, v34
	v_pk_fma_f32 v[70:71], v[36:37], v[36:37], v[70:71] op_sel_hi:[1,1,0]
	v_mul_f32_e32 v74, v35, v35
	v_mov_b32_e32 v71, v72
	v_mul_f32_e32 v72, v39, v39
	v_pk_fma_f32 v[72:73], v[38:39], v[38:39], v[72:73] op_sel_hi:[1,1,0]
	s_nop 0
	v_mov_b32_e32 v73, v74
	v_pk_add_f32 v[70:71], v[70:71], v[72:73]
	s_nop 0
	v_pk_add_f32 v[68:69], v[68:69], v[70:71]
	s_nop 0
	v_add_f32_e32 v65, v68, v69
	ds_bpermute_b32 v67, v154, v65
	v_lshlrev_b32_e32 v68, 7, v66
	v_mov_b32_e32 v69, v193
	s_waitcnt lgkmcnt(0)
	v_add_f32_e32 v65, v65, v67
	v_fmamk_f32 v65, v65, 0x3c000000, v223
	v_rsq_f32_e32 v65, v65
	s_nop 0
	v_mul_f32_e32 v74, v162, v65
	v_ashrrev_i32_e32 v65, 31, v64
	v_lshl_add_u64 v[64:65], s[18:19], 0, v[64:65]
	v_lshlrev_b64 v[64:65], 12, v[64:65]
	v_lshl_add_u64 v[64:65], s[12:13], 0, v[64:65]
	v_lshl_add_u64 v[64:65], v[64:65], 0, s[20:21]
	v_lshl_add_u64 v[72:73], v[64:65], 0, v[68:69]
	s_waitcnt vmcnt(0)
; __device__ __forceinline__ unsigned cvt_pk_bf16(float lo, float hi) { f32x2 v = {lo, hi}; bf16x2_t b = __builtin_convertvector(v, bf16x2_t); return __builtin_bit_cast(unsigned, b); }
; __device__ __forceinline__ void unit(int b, int h, int qb, const Params& P, LAS unsigned char* lds, const int tid) {
;     ...
; #pragma unroll
;         for (int k = 0; k < 8; ++k) { const f32x4 g0 = *(const f32x4*)(gp + 8 * k) * rs, g1 = *(const f32x4*)(gp + 8 * k + 4) * rs; const f32x4 a0 = v4[2 * k] * g0, a1 = v4[2 * k + 1] * g1;
;             u32x4 w; w.x = cvt_pk_bf16(a0.x, a0.y); w.y = cvt_pk_bf16(a0.z, a0.w); w.z = cvt_pk_bf16(a1.x, a1.y); w.w = cvt_pk_bf16(a1.z, a1.w);
;             *(u32x4*)(op + 8 * k) = w; }
	v_mov_b32_e32 v64, v116
	v_mov_b32_e32 v65, v117
	v_mov_b32_e32 v66, v118
	v_mov_b32_e32 v67, v119
	v_mov_b32_e32 v68, v112
	v_mov_b32_e32 v69, v113
	v_mov_b32_e32 v70, v114
	v_mov_b32_e32 v71, v115
	v_pk_mul_f32 v[64:65], v[64:65], v[74:75] op_sel_hi:[1,0]
	v_pk_mul_f32 v[68:69], v[68:69], v[74:75] op_sel_hi:[1,0]
	v_pk_mul_f32 v[70:71], v[70:71], v[74:75] op_sel_hi:[1,0]
	v_pk_mul_f32 v[66:67], v[66:67], v[74:75] op_sel_hi:[1,0]
	v_pk_mul_f32 v[18:19], v[18:19], v[70:71]
	v_pk_mul_f32 v[16:17], v[16:17], v[68:69]
	v_pk_mul_f32 v[66:67], v[14:15], v[66:67]
	v_pk_mul_f32 v[14:15], v[12:13], v[64:65]
	v_cvt_pk_bf16_f32 v12, v16, v17
	v_cvt_pk_bf16_f32 v13, v18, v19
	v_cvt_pk_bf16_f32 v14, v14, v15
	v_cvt_pk_bf16_f32 v15, v66, v67
	global_store_dwordx4 v[72:73], v[12:15], off
	s_nop 1
	v_mov_b32_e32 v12, v124
	v_mov_b32_e32 v13, v125
	v_mov_b32_e32 v14, v126
	v_mov_b32_e32 v15, v127
	v_mov_b32_e32 v16, v120
	v_mov_b32_e32 v17, v121
	v_mov_b32_e32 v18, v122
	v_mov_b32_e32 v19, v123
	v_pk_mul_f32 v[12:13], v[12:13], v[74:75] op_sel_hi:[1,0]
	v_pk_mul_f32 v[16:17], v[16:17], v[74:75] op_sel_hi:[1,0]
	v_pk_mul_f32 v[18:19], v[18:19], v[74:75] op_sel_hi:[1,0]
	v_pk_mul_f32 v[14:15], v[14:15], v[74:75] op_sel_hi:[1,0]
	v_pk_mul_f32 v[6:7], v[6:7], v[18:19]
	v_pk_mul_f32 v[4:5], v[4:5], v[16:17]
	v_pk_mul_f32 v[14:15], v[2:3], v[14:15]
	v_pk_mul_f32 v[2:3], v[0:1], v[12:13]
	v_cvt_pk_bf16_f32 v0, v4, v5
	v_cvt_pk_bf16_f32 v1, v6, v7
	v_cvt_pk_bf16_f32 v2, v2, v3
	v_cvt_pk_bf16_f32 v3, v14, v15
	global_store_dwordx4 v[72:73], v[0:3], off offset:16
	s_nop 1
	v_mov_b32_e32 v0, v132
	v_mov_b32_e32 v1, v133
	v_mov_b32_e32 v2, v134
	v_mov_b32_e32 v3, v135
	v_mov_b32_e32 v4, v128
	v_mov_b32_e32 v5, v129
	v_mov_b32_e32 v6, v130
	v_mov_b32_e32 v7, v131
	v_pk_mul_f32 v[0:1], v[0:1], v[74:75] op_sel_hi:[1,0]
	v_pk_mul_f32 v[4:5], v[4:5], v[74:75] op_sel_hi:[1,0]
	v_pk_mul_f32 v[6:7], v[6:7], v[74:75] op_sel_hi:[1,0]
	v_pk_mul_f32 v[2:3], v[2:3], v[74:75] op_sel_hi:[1,0]
	v_pk_mul_f32 v[6:7], v[10:11], v[6:7]
	v_pk_mul_f32 v[4:5], v[8:9], v[4:5]
	v_pk_mul_f32 v[8:9], v[26:27], v[2:3]
	v_pk_mul_f32 v[2:3], v[24:25], v[0:1]
	v_cvt_pk_bf16_f32 v0, v4, v5
	v_cvt_pk_bf16_f32 v1, v6, v7
	v_cvt_pk_bf16_f32 v2, v2, v3
	v_cvt_pk_bf16_f32 v3, v8, v9
	global_store_dwordx4 v[72:73], v[0:3], off offset:32
	s_nop 1
	v_mov_b32_e32 v0, v180
	v_mov_b32_e32 v1, v181
	v_mov_b32_e32 v2, v182
	v_mov_b32_e32 v3, v183
	v_mov_b32_e32 v4, v176
	v_mov_b32_e32 v5, v177
	v_mov_b32_e32 v6, v178
	v_mov_b32_e32 v7, v179
	v_pk_mul_f32 v[0:1], v[0:1], v[74:75] op_sel_hi:[1,0]
	v_pk_mul_f32 v[4:5], v[4:5], v[74:75] op_sel_hi:[1,0]
	v_pk_mul_f32 v[6:7], v[6:7], v[74:75] op_sel_hi:[1,0]
	v_pk_mul_f32 v[2:3], v[2:3], v[74:75] op_sel_hi:[1,0]
	v_pk_mul_f32 v[6:7], v[22:23], v[6:7]
	v_pk_mul_f32 v[4:5], v[20:21], v[4:5]
	v_pk_mul_f32 v[8:9], v[30:31], v[2:3]
	v_pk_mul_f32 v[2:3], v[28:29], v[0:1]
	v_cvt_pk_bf16_f32 v0, v4, v5
	v_cvt_pk_bf16_f32 v1, v6, v7
	v_cvt_pk_bf16_f32 v2, v2, v3
	v_cvt_pk_bf16_f32 v3, v8, v9
	global_store_dwordx4 v[72:73], v[0:3], off offset:48
	s_nop 1
	v_mov_b32_e32 v0, v188
	v_mov_b32_e32 v1, v189
	v_mov_b32_e32 v2, v190
	v_mov_b32_e32 v3, v191
	v_mov_b32_e32 v4, v184
	v_mov_b32_e32 v5, v185
	v_mov_b32_e32 v6, v186
	v_mov_b32_e32 v7, v187
	v_pk_mul_f32 v[0:1], v[74:75], v[0:1] op_sel_hi:[0,1]
	v_pk_mul_f32 v[4:5], v[74:75], v[4:5] op_sel_hi:[0,1]
	v_pk_mul_f32 v[6:7], v[74:75], v[6:7] op_sel_hi:[0,1]
	v_pk_mul_f32 v[2:3], v[74:75], v[2:3] op_sel_hi:[0,1]
	v_pk_mul_f32 v[6:7], v[46:47], v[6:7]
	v_pk_mul_f32 v[4:5], v[44:45], v[4:5]
	v_pk_mul_f32 v[8:9], v[54:55], v[2:3]
	v_pk_mul_f32 v[2:3], v[52:53], v[0:1]
	v_cvt_pk_bf16_f32 v0, v4, v5
	v_cvt_pk_bf16_f32 v1, v6, v7
	v_cvt_pk_bf16_f32 v2, v2, v3
	v_cvt_pk_bf16_f32 v3, v8, v9
	global_store_dwordx4 v[72:73], v[0:3], off offset:64
	s_nop 1
	v_mov_b32_e32 v0, v212
	v_mov_b32_e32 v1, v213
	v_mov_b32_e32 v2, v214
	v_mov_b32_e32 v3, v215
	v_mov_b32_e32 v4, v208
	v_mov_b32_e32 v5, v209
	v_mov_b32_e32 v6, v210
	v_mov_b32_e32 v7, v211
	v_pk_mul_f32 v[0:1], v[74:75], v[0:1] op_sel_hi:[0,1]
	v_pk_mul_f32 v[4:5], v[74:75], v[4:5] op_sel_hi:[0,1]
	v_pk_mul_f32 v[6:7], v[74:75], v[6:7] op_sel_hi:[0,1]
	v_pk_mul_f32 v[2:3], v[74:75], v[2:3] op_sel_hi:[0,1]
	v_pk_mul_f32 v[6:7], v[58:59], v[6:7]
	v_pk_mul_f32 v[4:5], v[56:57], v[4:5]
	v_pk_mul_f32 v[8:9], v[62:63], v[2:3]
	v_pk_mul_f32 v[2:3], v[60:61], v[0:1]
	v_cvt_pk_bf16_f32 v0, v4, v5
	v_cvt_pk_bf16_f32 v1, v6, v7
	v_cvt_pk_bf16_f32 v2, v2, v3
	v_cvt_pk_bf16_f32 v3, v8, v9
	global_store_dwordx4 v[72:73], v[0:3], off offset:80
	s_nop 1
	v_mov_b32_e32 v0, v232
	v_mov_b32_e32 v1, v233
	v_mov_b32_e32 v2, v234
	v_mov_b32_e32 v3, v235
	v_mov_b32_e32 v4, v216
	v_mov_b32_e32 v5, v217
	v_mov_b32_e32 v6, v218
	v_mov_b32_e32 v7, v219
	v_pk_mul_f32 v[0:1], v[74:75], v[0:1] op_sel_hi:[0,1]
	v_pk_mul_f32 v[4:5], v[74:75], v[4:5] op_sel_hi:[0,1]
	v_pk_mul_f32 v[6:7], v[74:75], v[6:7] op_sel_hi:[0,1]
	v_pk_mul_f32 v[2:3], v[74:75], v[2:3] op_sel_hi:[0,1]
	v_pk_mul_f32 v[6:7], v[42:43], v[6:7]
	v_pk_mul_f32 v[4:5], v[40:41], v[4:5]
	v_pk_mul_f32 v[8:9], v[50:51], v[2:3]
	v_pk_mul_f32 v[2:3], v[48:49], v[0:1]
	v_cvt_pk_bf16_f32 v0, v4, v5
	v_cvt_pk_bf16_f32 v1, v6, v7
	v_cvt_pk_bf16_f32 v2, v2, v3
	v_cvt_pk_bf16_f32 v3, v8, v9
	global_store_dwordx4 v[72:73], v[0:3], off offset:96
	s_nop 1
	v_mov_b32_e32 v0, v240
	v_mov_b32_e32 v1, v241
	v_mov_b32_e32 v2, v242
	v_mov_b32_e32 v3, v243
	v_mov_b32_e32 v4, v236
	v_mov_b32_e32 v5, v237
	v_mov_b32_e32 v6, v238
	v_mov_b32_e32 v7, v239
	v_pk_mul_f32 v[0:1], v[74:75], v[0:1] op_sel_hi:[0,1]
	v_pk_mul_f32 v[4:5], v[74:75], v[4:5] op_sel_hi:[0,1]
	v_pk_mul_f32 v[6:7], v[74:75], v[6:7] op_sel_hi:[0,1]
	v_pk_mul_f32 v[2:3], v[74:75], v[2:3] op_sel_hi:[0,1]
	v_pk_mul_f32 v[6:7], v[38:39], v[6:7]
	v_pk_mul_f32 v[4:5], v[36:37], v[4:5]
	v_pk_mul_f32 v[8:9], v[34:35], v[2:3]
	v_pk_mul_f32 v[2:3], v[32:33], v[0:1]
	v_cvt_pk_bf16_f32 v0, v4, v5
	v_cvt_pk_bf16_f32 v1, v6, v7
	v_cvt_pk_bf16_f32 v2, v2, v3
	v_cvt_pk_bf16_f32 v3, v8, v9
	global_store_dwordx4 v[72:73], v[0:3], off offset:112
	s_nop 1
	s_branch .LBB0_35
